# v93 + D-phase GEMM loops: per-segment s_setprio toggles removed, one static priority raise for waves 4-7 over the D phases instead
# baseline (speedup 1.0000x reference)
.LBB0_436:
	v_readfirstlane_b32 s99, v0
	s_cmp_lt_u32 s99, 0x100
	s_cbranch_scc1 .Lprio_skip4
	s_setprio 1
.Lprio_skip4:
	s_cmp_gt_i32 s18, 4
	s_cselect_b64 s[8:9], -1, 0
	s_cmp_lt_i32 s19, 5
	s_cselect_b64 s[2:3], -1, 0
	s_or_b64 s[2:3], s[8:9], s[2:3]
	s_and_b64 vcc, exec, s[2:3]
	s_cbranch_vccnz .LBB0_717
	s_andn2_b64 vcc, exec, s[20:21]
	s_cbranch_vccnz .LBB0_439
	s_cbranch_execz .LBB0_440
	s_branch .LBB0_493

.LBB0_510:
	v_mov_b32_e32 v162, v0
	s_nop 0
	v_and_b32_e32 v165, 14, v162
	v_ashrrev_i32_e32 v166, 1, v162
	v_and_or_b32 v165, v166, s38, v165
	v_lshlrev_b32_e32 v166, 3, v162
	v_and_b32_e32 v183, 8, v166
	v_lshrrev_b32_e32 v166, 1, v162
	v_and_b32_e32 v166, 0x67, v166
	v_bfe_u32 v182, v162, 4, 2
	v_bfe_u32 v162, v162, 1, 3
	v_lshlrev_b32_e32 v167, 8, v166
	v_or_b32_e32 v168, 8, v166
	v_bitop3_b32 v166, v166, 15, 8 bitop3:0xc8
	v_bitop3_b32 v162, v183, v162, v182 bitop3:0x36
	v_bitop3_b32 v166, v183, v166, v182 bitop3:0x36
	v_lshlrev_b32_e32 v168, 8, v168
	v_ashrrev_i32_e32 v165, 1, v165
	v_lshl_or_b32 v162, v162, 4, v167
	v_lshl_or_b32 v178, v166, 4, v168
	v_or_b32_e32 v185, 8, v165
	ds_read_b128 v[166:169], v162 offset:32768
	ds_read_b128 v[170:173], v162 offset:36864
	ds_read_b128 v[174:177], v178 offset:32768
	ds_read_b128 v[178:181], v178 offset:36864
	v_or_b32_e32 v162, v183, v182
	v_lshlrev_b32_e32 v184, 8, v165
	v_lshlrev_b32_e32 v186, 8, v185
	v_bitop3_b32 v165, v165, v162, 7 bitop3:0x6c
	v_bitop3_b32 v162, v185, v162, 15 bitop3:0x6c
	v_lshl_or_b32 v162, v162, 4, v186
	v_lshl_or_b32 v165, v165, 4, v184
	ds_read_b128 v[182:185], v162
	ds_read_b128 v[186:189], v165
	ds_read_b128 v[190:193], v165 offset:4096
	s_waitcnt lgkmcnt(1)
	v_mfma_f32_16x16x32_bf16 v[126:129], v[166:169], v[186:189], v[126:129]
	v_mfma_f32_16x16x32_bf16 v[122:125], v[174:177], v[186:189], v[122:125]
	v_mfma_f32_16x16x32_bf16 v[118:121], v[170:173], v[186:189], v[118:121]
	v_mfma_f32_16x16x32_bf16 v[114:117], v[178:181], v[186:189], v[114:117]
	ds_read_b128 v[186:189], v162 offset:4096
	ds_read_b128 v[194:197], v165 offset:8192
	v_mfma_f32_16x16x32_bf16 v[110:113], v[166:169], v[182:185], v[110:113]
	v_mfma_f32_16x16x32_bf16 v[106:109], v[174:177], v[182:185], v[106:109]
	v_mfma_f32_16x16x32_bf16 v[102:105], v[170:173], v[182:185], v[102:105]
	v_mfma_f32_16x16x32_bf16 v[98:101], v[178:181], v[182:185], v[98:101]
	s_waitcnt lgkmcnt(2)
	v_mfma_f32_16x16x32_bf16 v[94:97], v[166:169], v[190:193], v[94:97]
	v_mfma_f32_16x16x32_bf16 v[90:93], v[174:177], v[190:193], v[90:93]
	v_mfma_f32_16x16x32_bf16 v[86:89], v[170:173], v[190:193], v[86:89]
	v_mfma_f32_16x16x32_bf16 v[82:85], v[178:181], v[190:193], v[82:85]
	s_waitcnt lgkmcnt(1)
	v_mfma_f32_16x16x32_bf16 v[78:81], v[166:169], v[186:189], v[78:81]
	v_mfma_f32_16x16x32_bf16 v[74:77], v[174:177], v[186:189], v[74:77]
	v_mfma_f32_16x16x32_bf16 v[70:73], v[170:173], v[186:189], v[70:73]
	v_mfma_f32_16x16x32_bf16 v[182:185], v[178:181], v[186:189], v[42:45]
	s_waitcnt lgkmcnt(0)
	v_mfma_f32_16x16x32_bf16 v[66:69], v[166:169], v[194:197], v[66:69]
	v_mfma_f32_16x16x32_bf16 v[186:189], v[174:177], v[194:197], v[62:65]
	v_mfma_f32_16x16x32_bf16 v[190:193], v[170:173], v[194:197], v[58:61]
	v_mfma_f32_16x16x32_bf16 v[194:197], v[178:181], v[194:197], v[54:57]
	ds_read_b128 v[42:45], v162 offset:8192
	s_nop 1
	ds_read_b128 v[54:57], v165 offset:12288
	s_waitcnt lgkmcnt(1)
	v_mfma_f32_16x16x32_bf16 v[206:209], v[170:173], v[42:45], v[38:41]
	s_nop 2
	ds_read_b128 v[38:41], v162 offset:12288
	v_mfma_f32_16x16x32_bf16 v[198:201], v[166:169], v[42:45], v[50:53]
	v_mfma_f32_16x16x32_bf16 v[202:205], v[174:177], v[42:45], v[46:49]
	v_mfma_f32_16x16x32_bf16 v[210:213], v[178:181], v[42:45], v[34:37]
	s_waitcnt lgkmcnt(1)
	v_mfma_f32_16x16x32_bf16 v[214:217], v[166:169], v[54:57], v[30:33]
	v_mfma_f32_16x16x32_bf16 v[218:221], v[174:177], v[54:57], v[26:29]
	v_mfma_f32_16x16x32_bf16 v[222:225], v[170:173], v[54:57], v[22:25]
	v_mfma_f32_16x16x32_bf16 v[226:229], v[178:181], v[54:57], v[18:21]
	s_waitcnt lgkmcnt(0)
	v_mfma_f32_16x16x32_bf16 v[166:169], v[166:169], v[38:41], v[14:17]
	v_mfma_f32_16x16x32_bf16 v[174:177], v[174:177], v[38:41], v[10:13]
	v_mfma_f32_16x16x32_bf16 v[170:173], v[170:173], v[38:41], v[6:9]
	v_mfma_f32_16x16x32_bf16 v[178:181], v[178:181], v[38:41], v[2:5]
	s_nop 1
	v_mov_b32_e32 v2, v0
	s_nop 0
	v_and_b32_e32 v3, 14, v2
	v_ashrrev_i32_e32 v5, 1, v2
	v_and_or_b32 v3, v5, s38, v3
	v_lshlrev_b32_e32 v5, 3, v2
	v_bfe_u32 v4, v2, 4, 2
	v_and_b32_e32 v5, 8, v5
	v_lshrrev_b32_e32 v9, 1, v2
	v_ashrrev_i32_e32 v3, 1, v3
	v_or_b32_e32 v6, v5, v4
	v_and_b32_e32 v9, 0x67, v9
	v_bfe_u32 v2, v2, 1, 3
	v_bitop3_b32 v7, v3, v6, 7 bitop3:0x6c
	v_lshlrev_b32_e32 v8, 8, v3
	v_or_b32_e32 v3, 8, v3
	v_bitop3_b32 v2, v5, v2, v4 bitop3:0x36
	v_lshlrev_b32_e32 v10, 8, v9
	v_or_b32_e32 v11, 8, v9
	v_bitop3_b32 v9, v9, 15, 8 bitop3:0xc8
	v_bitop3_b32 v6, v3, v6, 15 bitop3:0x6c
	v_lshlrev_b32_e32 v2, 4, v2
	v_bitop3_b32 v4, v5, v9, v4 bitop3:0x36
	v_lshlrev_b32_e32 v3, 8, v3
	v_lshlrev_b32_e32 v6, 4, v6
	v_lshlrev_b32_e32 v5, 8, v11
	v_lshlrev_b32_e32 v4, 4, v4
	v_bitop3_b32 v2, v2, 64, v10 bitop3:0x36
	v_lshlrev_b32_e32 v7, 4, v7
	v_bitop3_b32 v4, v4, 64, v5 bitop3:0x36
	ds_read_b128 v[230:233], v2 offset:32768
	ds_read_b128 v[234:237], v2 offset:36864
	ds_read_b128 v[238:241], v4 offset:32768
	ds_read_b128 v[242:245], v4 offset:36864
	v_bitop3_b32 v165, v6, 64, v3 bitop3:0x36
	v_bitop3_b32 v162, v7, 64, v8 bitop3:0x36
	ds_read_b128 v[30:33], v165
	ds_read_b128 v[14:17], v162
	ds_read_b128 v[46:49], v162 offset:4096
	s_waitcnt lgkmcnt(2)
	v_mfma_f32_16x16x32_bf16 v[26:29], v[234:237], v[30:33], v[102:105]
	ds_read_b128 v[62:65], v165 offset:4096
	s_nop 1
	ds_read_b128 v[102:105], v162 offset:8192
	s_waitcnt lgkmcnt(3)
	v_mfma_f32_16x16x32_bf16 v[2:5], v[230:233], v[14:17], v[126:129]
	v_mfma_f32_16x16x32_bf16 v[6:9], v[238:241], v[14:17], v[122:125]
	v_mfma_f32_16x16x32_bf16 v[10:13], v[234:237], v[14:17], v[118:121]
	v_mfma_f32_16x16x32_bf16 v[14:17], v[242:245], v[14:17], v[114:117]
	v_mfma_f32_16x16x32_bf16 v[18:21], v[230:233], v[30:33], v[110:113]
	v_mfma_f32_16x16x32_bf16 v[22:25], v[238:241], v[30:33], v[106:109]
	v_mfma_f32_16x16x32_bf16 v[30:33], v[242:245], v[30:33], v[98:101]
	s_waitcnt lgkmcnt(2)
	v_mfma_f32_16x16x32_bf16 v[34:37], v[230:233], v[46:49], v[94:97]
	s_nop 2
	ds_read_b128 v[94:97], v165 offset:8192
	ds_read_b128 v[110:113], v162 offset:12288
	ds_read_b128 v[126:129], v165 offset:12288
	v_mfma_f32_16x16x32_bf16 v[38:41], v[238:241], v[46:49], v[90:93]
	v_mfma_f32_16x16x32_bf16 v[42:45], v[234:237], v[46:49], v[86:89]
	v_mfma_f32_16x16x32_bf16 v[46:49], v[242:245], v[46:49], v[82:85]
	s_waitcnt lgkmcnt(4)
	v_mfma_f32_16x16x32_bf16 v[50:53], v[230:233], v[62:65], v[78:81]
	v_mfma_f32_16x16x32_bf16 v[54:57], v[238:241], v[62:65], v[74:77]
	v_mfma_f32_16x16x32_bf16 v[58:61], v[234:237], v[62:65], v[70:73]
	v_mfma_f32_16x16x32_bf16 v[62:65], v[242:245], v[62:65], v[182:185]
	s_waitcnt lgkmcnt(3)
	v_mfma_f32_16x16x32_bf16 v[66:69], v[230:233], v[102:105], v[66:69]
	v_mfma_f32_16x16x32_bf16 v[70:73], v[238:241], v[102:105], v[186:189]
	v_mfma_f32_16x16x32_bf16 v[74:77], v[234:237], v[102:105], v[190:193]
	v_mfma_f32_16x16x32_bf16 v[78:81], v[242:245], v[102:105], v[194:197]
	s_waitcnt lgkmcnt(2)
	v_mfma_f32_16x16x32_bf16 v[82:85], v[230:233], v[94:97], v[198:201]
	v_mfma_f32_16x16x32_bf16 v[86:89], v[238:241], v[94:97], v[202:205]
	v_mfma_f32_16x16x32_bf16 v[90:93], v[234:237], v[94:97], v[206:209]
	v_mfma_f32_16x16x32_bf16 v[94:97], v[242:245], v[94:97], v[210:213]
	s_waitcnt lgkmcnt(1)
	v_mfma_f32_16x16x32_bf16 v[98:101], v[230:233], v[110:113], v[214:217]
	v_mfma_f32_16x16x32_bf16 v[102:105], v[238:241], v[110:113], v[218:221]
	v_mfma_f32_16x16x32_bf16 v[106:109], v[234:237], v[110:113], v[222:225]
	v_mfma_f32_16x16x32_bf16 v[110:113], v[242:245], v[110:113], v[226:229]
	s_waitcnt lgkmcnt(0)
	v_mfma_f32_16x16x32_bf16 v[114:117], v[230:233], v[126:129], v[166:169]
	v_mfma_f32_16x16x32_bf16 v[118:121], v[238:241], v[126:129], v[174:177]
	v_mfma_f32_16x16x32_bf16 v[122:125], v[234:237], v[126:129], v[170:173]
	v_mfma_f32_16x16x32_bf16 v[126:129], v[242:245], v[126:129], v[178:181]
	s_add_i32 s3, s36, -1
	s_cmp_ge_u32 s3, s30
	s_cbranch_scc1 .LBB0_512
	v_mov_b32_e32 v162, v0
	s_nop 0
	v_ashrrev_i32_e32 v165, 4, v162
	v_xor_b32_e32 v162, v165, v162
	v_lshlrev_b32_e32 v162, 4, v162
	v_and_b32_e32 v162, 0xf0, v162
	v_lshl_or_b32 v162, v165, 8, v162
	v_add_u32_e32 v162, 0x10000, v162
	s_waitcnt vmcnt(5)
	ds_write_b128 v162, v[142:145]
	ds_write_b128 v162, v[130:133] offset:8192
	ds_write_b128 v162, v[134:137] offset:16384
	s_waitcnt vmcnt(3)
	ds_write_b128 v162, v[146:149] offset:24576
	ds_write_b128 v162, v[138:141] offset:32768
	s_waitcnt vmcnt(2)
	ds_write_b128 v162, v[150:153] offset:40960
	s_waitcnt vmcnt(1)
	ds_write_b128 v162, v[154:157] offset:49152
	s_waitcnt vmcnt(0)
	ds_write_b128 v162, v[158:161] offset:57344

.LBB0_520:
	v_mov_b32_e32 v162, v0
	s_nop 0
	v_and_b32_e32 v165, 14, v162
	v_ashrrev_i32_e32 v166, 1, v162
	v_and_or_b32 v165, v166, s38, v165
	v_lshlrev_b32_e32 v166, 3, v162
	v_and_b32_e32 v183, 8, v166
	v_lshrrev_b32_e32 v166, 1, v162
	v_and_b32_e32 v166, 0x67, v166
	v_bfe_u32 v182, v162, 4, 2
	v_bfe_u32 v162, v162, 1, 3
	v_lshlrev_b32_e32 v167, 8, v166
	v_or_b32_e32 v168, 8, v166
	v_bitop3_b32 v166, v166, 15, 8 bitop3:0xc8
	v_bitop3_b32 v162, v183, v162, v182 bitop3:0x36
	v_bitop3_b32 v166, v183, v166, v182 bitop3:0x36
	v_lshlrev_b32_e32 v168, 8, v168
	v_lshl_or_b32 v162, v162, 4, v167
	v_lshl_or_b32 v174, v166, 4, v168
	v_ashrrev_i32_e32 v165, 1, v165
	v_or_b32_e32 v167, 0x18000, v162
	v_or_b32_e32 v170, 0x18000, v174
	v_or_b32_e32 v162, 0x19000, v162
	v_or_b32_e32 v178, 0x19000, v174
	v_or_b32_e32 v184, 8, v165
	ds_read_b128 v[166:169], v167
	ds_read_b128 v[170:173], v170
	ds_read_b128 v[174:177], v162
	ds_read_b128 v[178:181], v178
	v_or_b32_e32 v162, v183, v182
	v_bitop3_b32 v182, v165, v162, 7 bitop3:0x6c
	v_bitop3_b32 v162, v184, v162, 15 bitop3:0x6c
	v_lshlrev_b32_e32 v162, 4, v162
	v_lshlrev_b32_e32 v182, 4, v182
	v_lshl_or_b32 v162, v184, 8, v162
	v_lshl_or_b32 v165, v165, 8, v182
	v_add_u32_e32 v162, 0x10000, v162
	v_add_u32_e32 v165, 0x10000, v165
	ds_read_b128 v[182:185], v162
	ds_read_b128 v[186:189], v165
	ds_read_b128 v[190:193], v165 offset:4096
	s_waitcnt lgkmcnt(1)
	v_mfma_f32_16x16x32_bf16 v[2:5], v[166:169], v[186:189], v[2:5]
	v_mfma_f32_16x16x32_bf16 v[6:9], v[170:173], v[186:189], v[6:9]
	v_mfma_f32_16x16x32_bf16 v[10:13], v[174:177], v[186:189], v[10:13]
	v_mfma_f32_16x16x32_bf16 v[14:17], v[178:181], v[186:189], v[14:17]
	ds_read_b128 v[186:189], v162 offset:4096
	ds_read_b128 v[194:197], v165 offset:8192
	v_mfma_f32_16x16x32_bf16 v[18:21], v[166:169], v[182:185], v[18:21]
	v_mfma_f32_16x16x32_bf16 v[22:25], v[170:173], v[182:185], v[22:25]
	v_mfma_f32_16x16x32_bf16 v[26:29], v[174:177], v[182:185], v[26:29]
	v_mfma_f32_16x16x32_bf16 v[30:33], v[178:181], v[182:185], v[30:33]
	s_waitcnt lgkmcnt(2)
	v_mfma_f32_16x16x32_bf16 v[34:37], v[166:169], v[190:193], v[34:37]
	v_mfma_f32_16x16x32_bf16 v[38:41], v[170:173], v[190:193], v[38:41]
	v_mfma_f32_16x16x32_bf16 v[42:45], v[174:177], v[190:193], v[42:45]
	v_mfma_f32_16x16x32_bf16 v[46:49], v[178:181], v[190:193], v[46:49]
	s_waitcnt lgkmcnt(1)
	v_mfma_f32_16x16x32_bf16 v[50:53], v[166:169], v[186:189], v[50:53]
	v_mfma_f32_16x16x32_bf16 v[54:57], v[170:173], v[186:189], v[54:57]
	v_mfma_f32_16x16x32_bf16 v[58:61], v[174:177], v[186:189], v[58:61]
	v_mfma_f32_16x16x32_bf16 v[62:65], v[178:181], v[186:189], v[62:65]
	s_waitcnt lgkmcnt(0)
	v_mfma_f32_16x16x32_bf16 v[182:185], v[170:173], v[194:197], v[70:73]
	v_mfma_f32_16x16x32_bf16 v[186:189], v[174:177], v[194:197], v[74:77]
	s_nop 1
	ds_read_b128 v[70:73], v162 offset:8192
	ds_read_b128 v[74:77], v165 offset:12288
	v_mfma_f32_16x16x32_bf16 v[190:193], v[178:181], v[194:197], v[78:81]
	s_nop 2
	ds_read_b128 v[78:81], v162 offset:12288
	v_mfma_f32_16x16x32_bf16 v[66:69], v[166:169], v[194:197], v[66:69]
	s_waitcnt lgkmcnt(2)
	v_mfma_f32_16x16x32_bf16 v[194:197], v[166:169], v[70:73], v[82:85]
	v_mfma_f32_16x16x32_bf16 v[198:201], v[170:173], v[70:73], v[86:89]
	v_mfma_f32_16x16x32_bf16 v[202:205], v[174:177], v[70:73], v[90:93]
	v_mfma_f32_16x16x32_bf16 v[206:209], v[178:181], v[70:73], v[94:97]
	s_waitcnt lgkmcnt(1)
	v_mfma_f32_16x16x32_bf16 v[210:213], v[166:169], v[74:77], v[98:101]
	v_mfma_f32_16x16x32_bf16 v[214:217], v[170:173], v[74:77], v[102:105]
	v_mfma_f32_16x16x32_bf16 v[218:221], v[174:177], v[74:77], v[106:109]
	v_mfma_f32_16x16x32_bf16 v[222:225], v[178:181], v[74:77], v[110:113]
	s_waitcnt lgkmcnt(0)
	v_mfma_f32_16x16x32_bf16 v[166:169], v[166:169], v[78:81], v[114:117]
	v_mfma_f32_16x16x32_bf16 v[170:173], v[170:173], v[78:81], v[118:121]
	v_mfma_f32_16x16x32_bf16 v[174:177], v[174:177], v[78:81], v[122:125]
	v_mfma_f32_16x16x32_bf16 v[178:181], v[178:181], v[78:81], v[126:129]
	v_mov_b32_e32 v70, v0
	s_nop 0
	v_and_b32_e32 v71, 14, v70
	v_ashrrev_i32_e32 v73, 1, v70
	v_and_or_b32 v71, v73, s38, v71
	v_lshlrev_b32_e32 v73, 3, v70
	v_bfe_u32 v72, v70, 4, 2
	v_and_b32_e32 v73, 8, v73
	v_ashrrev_i32_e32 v71, 1, v71
	v_or_b32_e32 v74, v73, v72
	v_bitop3_b32 v75, v71, v74, 7 bitop3:0x6c
	v_lshlrev_b32_e32 v76, 8, v71
	v_or_b32_e32 v71, 8, v71
	v_bitop3_b32 v74, v71, v74, 15 bitop3:0x6c
	v_lshlrev_b32_e32 v71, 8, v71
	v_lshl_or_b32 v71, v74, 4, v71
	v_lshrrev_b32_e32 v74, 1, v70
	v_and_b32_e32 v74, 0x67, v74
	v_bfe_u32 v70, v70, 1, 3
	v_lshl_or_b32 v75, v75, 4, v76
	v_bitop3_b32 v70, v73, v70, v72 bitop3:0x36
	v_lshlrev_b32_e32 v76, 8, v74
	v_lshl_or_b32 v70, v70, 4, v76
	v_or_b32_e32 v76, 8, v74
	v_bitop3_b32 v74, v74, 15, 8 bitop3:0xc8
	v_bitop3_b32 v72, v73, v74, v72 bitop3:0x36
	v_lshlrev_b32_e32 v73, 8, v76
	v_lshl_or_b32 v72, v72, 4, v73
	v_bitop3_b32 v73, v70, s31, v1 bitop3:0xde
	v_bitop3_b32 v74, v72, s31, v1 bitop3:0xde
	v_bitop3_b32 v70, v70, s39, v1 bitop3:0xde
	v_bitop3_b32 v72, v72, s39, v1 bitop3:0xde
	v_xad_u32 v165, v71, 64, v164
	ds_read_b128 v[226:229], v73
	ds_read_b128 v[230:233], v74
	ds_read_b128 v[234:237], v70
	ds_read_b128 v[238:241], v72
	v_xad_u32 v162, v75, 64, v164
	ds_read_b128 v[70:73], v165
	ds_read_b128 v[74:77], v162
	ds_read_b128 v[78:81], v162 offset:4096
	s_waitcnt lgkmcnt(1)
	v_mfma_f32_16x16x32_bf16 v[126:129], v[226:229], v[74:77], v[2:5]
	v_mfma_f32_16x16x32_bf16 v[122:125], v[230:233], v[74:77], v[6:9]
	s_nop 1
	ds_read_b128 v[2:5], v165 offset:4096
	ds_read_b128 v[6:9], v162 offset:8192
	v_mfma_f32_16x16x32_bf16 v[118:121], v[234:237], v[74:77], v[10:13]
	v_mfma_f32_16x16x32_bf16 v[114:117], v[238:241], v[74:77], v[14:17]
	v_mfma_f32_16x16x32_bf16 v[110:113], v[226:229], v[70:73], v[18:21]
	v_mfma_f32_16x16x32_bf16 v[106:109], v[230:233], v[70:73], v[22:25]
	v_mfma_f32_16x16x32_bf16 v[102:105], v[234:237], v[70:73], v[26:29]
	v_mfma_f32_16x16x32_bf16 v[98:101], v[238:241], v[70:73], v[30:33]
	s_waitcnt lgkmcnt(2)
	v_mfma_f32_16x16x32_bf16 v[94:97], v[226:229], v[78:81], v[34:37]
	v_mfma_f32_16x16x32_bf16 v[90:93], v[230:233], v[78:81], v[38:41]
	v_mfma_f32_16x16x32_bf16 v[86:89], v[234:237], v[78:81], v[42:45]
	v_mfma_f32_16x16x32_bf16 v[82:85], v[238:241], v[78:81], v[46:49]
	s_waitcnt lgkmcnt(1)
	v_mfma_f32_16x16x32_bf16 v[78:81], v[226:229], v[2:5], v[50:53]
	v_mfma_f32_16x16x32_bf16 v[74:77], v[230:233], v[2:5], v[54:57]
	v_mfma_f32_16x16x32_bf16 v[70:73], v[234:237], v[2:5], v[58:61]
	v_mfma_f32_16x16x32_bf16 v[42:45], v[238:241], v[2:5], v[62:65]
	s_waitcnt lgkmcnt(0)
	v_mfma_f32_16x16x32_bf16 v[66:69], v[226:229], v[6:9], v[66:69]
	v_mfma_f32_16x16x32_bf16 v[62:65], v[230:233], v[6:9], v[182:185]
	v_mfma_f32_16x16x32_bf16 v[58:61], v[234:237], v[6:9], v[186:189]
	v_mfma_f32_16x16x32_bf16 v[54:57], v[238:241], v[6:9], v[190:193]
	ds_read_b128 v[2:5], v165 offset:8192
	ds_read_b128 v[6:9], v162 offset:12288
	ds_read_b128 v[182:185], v165 offset:12288
	s_waitcnt lgkmcnt(2)
	v_mfma_f32_16x16x32_bf16 v[50:53], v[226:229], v[2:5], v[194:197]
	v_mfma_f32_16x16x32_bf16 v[46:49], v[230:233], v[2:5], v[198:201]
	v_mfma_f32_16x16x32_bf16 v[38:41], v[234:237], v[2:5], v[202:205]
	v_mfma_f32_16x16x32_bf16 v[34:37], v[238:241], v[2:5], v[206:209]
	s_waitcnt lgkmcnt(1)
	v_mfma_f32_16x16x32_bf16 v[30:33], v[226:229], v[6:9], v[210:213]
	v_mfma_f32_16x16x32_bf16 v[26:29], v[230:233], v[6:9], v[214:217]
	v_mfma_f32_16x16x32_bf16 v[22:25], v[234:237], v[6:9], v[218:221]
	v_mfma_f32_16x16x32_bf16 v[18:21], v[238:241], v[6:9], v[222:225]
	s_waitcnt lgkmcnt(0)
	v_mfma_f32_16x16x32_bf16 v[14:17], v[226:229], v[182:185], v[166:169]
	v_mfma_f32_16x16x32_bf16 v[10:13], v[230:233], v[182:185], v[170:173]
	v_mfma_f32_16x16x32_bf16 v[6:9], v[234:237], v[182:185], v[174:177]
	v_mfma_f32_16x16x32_bf16 v[2:5], v[238:241], v[182:185], v[178:181]
	s_cmp_ge_u32 s36, s30
	s_cselect_b64 s[22:23], -1, 0
	s_and_b64 vcc, exec, s[22:23]
	s_cbranch_vccnz .LBB0_522
	v_mov_b32_e32 v162, v0
	s_nop 0
	v_ashrrev_i32_e32 v165, 4, v162
	v_xor_b32_e32 v162, v165, v162
	v_lshlrev_b32_e32 v165, 8, v165
	v_lshlrev_b32_e32 v162, 4, v162
	v_and_or_b32 v162, v162, s37, v165
	s_waitcnt vmcnt(5)
	ds_write_b128 v162, v[142:145]
	ds_write_b128 v162, v[130:133] offset:8192
	ds_write_b128 v162, v[134:137] offset:16384
	s_waitcnt vmcnt(3)
	ds_write_b128 v162, v[146:149] offset:24576
	ds_write_b128 v162, v[138:141] offset:32768
	s_waitcnt vmcnt(2)
	ds_write_b128 v162, v[150:153] offset:40960
	s_waitcnt vmcnt(1)
	ds_write_b128 v162, v[154:157] offset:49152
	s_waitcnt vmcnt(0)
	ds_write_b128 v162, v[158:161] offset:57344

.LBB0_612:
	v_mov_b32_e32 v3, v0
	s_nop 0
	v_and_b32_e32 v4, 14, v3
	v_ashrrev_i32_e32 v38, 1, v3
	v_and_or_b32 v4, v38, s51, v4
	v_lshlrev_b32_e32 v38, 3, v3
	v_and_b32_e32 v54, 8, v38
	v_lshrrev_b32_e32 v38, 1, v3
	v_and_b32_e32 v38, 0x67, v38
	v_bfe_u32 v5, v3, 4, 2
	v_bfe_u32 v3, v3, 1, 3
	v_lshlrev_b32_e32 v39, 8, v38
	v_or_b32_e32 v40, 8, v38
	v_bitop3_b32 v38, v38, 15, 8 bitop3:0xc8
	v_bitop3_b32 v3, v54, v3, v5 bitop3:0x36
	v_bitop3_b32 v38, v54, v38, v5 bitop3:0x36
	v_lshlrev_b32_e32 v40, 8, v40
	v_ashrrev_i32_e32 v4, 1, v4
	v_lshl_or_b32 v3, v3, 4, v39
	v_lshl_or_b32 v50, v38, 4, v40
	v_or_b32_e32 v56, 8, v4
	ds_read_b128 v[38:41], v3 offset:32768
	ds_read_b128 v[42:45], v3 offset:36864
	ds_read_b128 v[46:49], v50 offset:32768
	ds_read_b128 v[50:53], v50 offset:36864
	v_or_b32_e32 v3, v54, v5
	v_lshlrev_b32_e32 v55, 8, v4
	v_lshlrev_b32_e32 v57, 8, v56
	v_bitop3_b32 v4, v4, v3, 7 bitop3:0x6c
	v_bitop3_b32 v3, v56, v3, 15 bitop3:0x6c
	v_lshl_or_b32 v162, v3, 4, v57
	v_lshl_or_b32 v150, v4, 4, v55
	ds_read_b128 v[54:57], v162
	ds_read_b128 v[58:61], v150
	ds_read_b128 v[62:65], v150 offset:4096
	v_mov_b32_e32 v3, v2
	v_mov_b32_e32 v4, v2
	v_mov_b32_e32 v5, v2
	ds_read_b128 v[90:93], v162 offset:4096
	ds_read_b128 v[94:97], v150 offset:8192
	s_waitcnt lgkmcnt(3)
	v_mfma_f32_16x16x32_bf16 v[66:69], v[38:41], v[58:61], v[2:5]
	v_mfma_f32_16x16x32_bf16 v[70:73], v[46:49], v[58:61], v[2:5]
	v_mfma_f32_16x16x32_bf16 v[74:77], v[42:45], v[58:61], v[2:5]
	v_mfma_f32_16x16x32_bf16 v[58:61], v[50:53], v[58:61], v[2:5]
	v_mfma_f32_16x16x32_bf16 v[78:81], v[38:41], v[54:57], v[2:5]
	v_mfma_f32_16x16x32_bf16 v[82:85], v[46:49], v[54:57], v[2:5]
	v_mfma_f32_16x16x32_bf16 v[86:89], v[42:45], v[54:57], v[2:5]
	v_mfma_f32_16x16x32_bf16 v[98:101], v[50:53], v[54:57], v[2:5]
	s_waitcnt lgkmcnt(2)
	v_mfma_f32_16x16x32_bf16 v[102:105], v[38:41], v[62:65], v[2:5]
	v_mfma_f32_16x16x32_bf16 v[106:109], v[46:49], v[62:65], v[2:5]
	v_mfma_f32_16x16x32_bf16 v[110:113], v[42:45], v[62:65], v[2:5]
	v_mfma_f32_16x16x32_bf16 v[114:117], v[50:53], v[62:65], v[2:5]
	ds_read_b128 v[54:57], v162 offset:8192
	ds_read_b128 v[62:65], v150 offset:12288
	s_waitcnt lgkmcnt(3)
	v_mfma_f32_16x16x32_bf16 v[118:121], v[38:41], v[90:93], v[2:5]
	v_mfma_f32_16x16x32_bf16 v[122:125], v[46:49], v[90:93], v[2:5]
	v_mfma_f32_16x16x32_bf16 v[126:129], v[42:45], v[90:93], v[2:5]
	v_mfma_f32_16x16x32_bf16 v[130:133], v[50:53], v[90:93], v[2:5]
	ds_read_b128 v[90:93], v162 offset:12288
	s_waitcnt lgkmcnt(3)
	v_mfma_f32_16x16x32_bf16 v[134:137], v[38:41], v[94:97], v[2:5]
	v_mfma_f32_16x16x32_bf16 v[138:141], v[46:49], v[94:97], v[2:5]
	v_mfma_f32_16x16x32_bf16 v[142:145], v[42:45], v[94:97], v[2:5]
	v_mfma_f32_16x16x32_bf16 v[146:149], v[50:53], v[94:97], v[2:5]
	s_waitcnt lgkmcnt(2)
	v_mfma_f32_16x16x32_bf16 v[150:153], v[38:41], v[54:57], v[2:5]
	v_mfma_f32_16x16x32_bf16 v[154:157], v[46:49], v[54:57], v[2:5]
	v_mfma_f32_16x16x32_bf16 v[158:161], v[42:45], v[54:57], v[2:5]
	v_mfma_f32_16x16x32_bf16 v[168:171], v[50:53], v[54:57], v[2:5]
	s_waitcnt lgkmcnt(1)
	v_mfma_f32_16x16x32_bf16 v[172:175], v[38:41], v[62:65], v[2:5]
	v_mfma_f32_16x16x32_bf16 v[176:179], v[46:49], v[62:65], v[2:5]
	v_mfma_f32_16x16x32_bf16 v[180:183], v[42:45], v[62:65], v[2:5]
	v_mfma_f32_16x16x32_bf16 v[184:187], v[50:53], v[62:65], v[2:5]
	s_waitcnt lgkmcnt(0)
	v_mfma_f32_16x16x32_bf16 v[188:191], v[38:41], v[90:93], v[2:5]
	v_mfma_f32_16x16x32_bf16 v[192:195], v[46:49], v[90:93], v[2:5]
	v_mfma_f32_16x16x32_bf16 v[196:199], v[42:45], v[90:93], v[2:5]
	v_mfma_f32_16x16x32_bf16 v[200:203], v[50:53], v[90:93], v[2:5]
	s_nop 1
	v_mov_b32_e32 v2, v0
	s_nop 0
	v_and_b32_e32 v3, 14, v2
	v_ashrrev_i32_e32 v5, 1, v2
	v_and_or_b32 v3, v5, s51, v3
	v_lshlrev_b32_e32 v5, 3, v2
	v_bfe_u32 v4, v2, 4, 2
	v_and_b32_e32 v5, 8, v5
	v_lshrrev_b32_e32 v41, 1, v2
	v_ashrrev_i32_e32 v3, 1, v3
	v_or_b32_e32 v38, v5, v4
	v_and_b32_e32 v41, 0x67, v41
	v_bfe_u32 v2, v2, 1, 3
	v_bitop3_b32 v39, v3, v38, 7 bitop3:0x6c
	v_lshlrev_b32_e32 v40, 8, v3
	v_or_b32_e32 v3, 8, v3
	v_bitop3_b32 v2, v5, v2, v4 bitop3:0x36
	v_lshlrev_b32_e32 v42, 8, v41
	v_or_b32_e32 v43, 8, v41
	v_bitop3_b32 v41, v41, 15, 8 bitop3:0xc8
	v_bitop3_b32 v38, v3, v38, 15 bitop3:0x6c
	v_lshlrev_b32_e32 v2, 4, v2
	v_bitop3_b32 v4, v5, v41, v4 bitop3:0x36
	v_lshlrev_b32_e32 v3, 8, v3
	v_lshlrev_b32_e32 v38, 4, v38
	v_lshlrev_b32_e32 v5, 8, v43
	v_lshlrev_b32_e32 v4, 4, v4
	v_bitop3_b32 v2, v2, 64, v42 bitop3:0x36
	v_lshlrev_b32_e32 v39, 4, v39
	v_bitop3_b32 v4, v4, 64, v5 bitop3:0x36
	ds_read_b128 v[204:207], v2 offset:32768
	ds_read_b128 v[208:211], v2 offset:36864
	ds_read_b128 v[212:215], v4 offset:32768
	ds_read_b128 v[216:219], v4 offset:36864
	v_bitop3_b32 v167, v38, 64, v3 bitop3:0x36
	v_bitop3_b32 v162, v39, 64, v40 bitop3:0x36
	ds_read_b128 v[62:65], v167
	ds_read_b128 v[46:49], v162
	ds_read_b128 v[90:93], v162 offset:4096
	ds_read_b128 v[94:97], v167 offset:4096
	ds_read_b128 v[220:223], v162 offset:8192
	s_waitcnt lgkmcnt(3)
	v_mfma_f32_16x16x32_bf16 v[2:5], v[204:207], v[46:49], v[66:69]
	v_mfma_f32_16x16x32_bf16 v[38:41], v[212:215], v[46:49], v[70:73]
	v_mfma_f32_16x16x32_bf16 v[42:45], v[208:211], v[46:49], v[74:77]
	v_mfma_f32_16x16x32_bf16 v[46:49], v[216:219], v[46:49], v[58:61]
	v_mfma_f32_16x16x32_bf16 v[50:53], v[204:207], v[62:65], v[78:81]
	v_mfma_f32_16x16x32_bf16 v[54:57], v[212:215], v[62:65], v[82:85]
	v_mfma_f32_16x16x32_bf16 v[58:61], v[208:211], v[62:65], v[86:89]
	v_mfma_f32_16x16x32_bf16 v[62:65], v[216:219], v[62:65], v[98:101]
	s_waitcnt lgkmcnt(2)
	v_mfma_f32_16x16x32_bf16 v[66:69], v[204:207], v[90:93], v[102:105]
	v_mfma_f32_16x16x32_bf16 v[70:73], v[212:215], v[90:93], v[106:109]
	v_mfma_f32_16x16x32_bf16 v[74:77], v[208:211], v[90:93], v[110:113]
	v_mfma_f32_16x16x32_bf16 v[78:81], v[216:219], v[90:93], v[114:117]
	s_waitcnt lgkmcnt(1)
	v_mfma_f32_16x16x32_bf16 v[90:93], v[208:211], v[94:97], v[126:129]
	s_waitcnt lgkmcnt(0)
	v_mfma_f32_16x16x32_bf16 v[106:109], v[208:211], v[220:223], v[142:145]
	s_nop 0
	ds_read_b128 v[126:129], v167 offset:8192
	s_nop 0
	ds_read_b128 v[142:145], v162 offset:12288
	v_mfma_f32_16x16x32_bf16 v[86:89], v[212:215], v[94:97], v[122:125]
	s_waitcnt lgkmcnt(1)
	v_mfma_f32_16x16x32_bf16 v[122:125], v[208:211], v[126:129], v[158:161]
	s_nop 2
	ds_read_b128 v[158:161], v167 offset:12288
	v_mfma_f32_16x16x32_bf16 v[82:85], v[204:207], v[94:97], v[118:121]
	v_mfma_f32_16x16x32_bf16 v[94:97], v[216:219], v[94:97], v[130:133]
	v_mfma_f32_16x16x32_bf16 v[98:101], v[204:207], v[220:223], v[134:137]
	v_mfma_f32_16x16x32_bf16 v[102:105], v[212:215], v[220:223], v[138:141]
	v_mfma_f32_16x16x32_bf16 v[110:113], v[216:219], v[220:223], v[146:149]
	v_mfma_f32_16x16x32_bf16 v[114:117], v[204:207], v[126:129], v[150:153]
	v_mfma_f32_16x16x32_bf16 v[118:121], v[212:215], v[126:129], v[154:157]
	v_mfma_f32_16x16x32_bf16 v[126:129], v[216:219], v[126:129], v[168:171]
	s_waitcnt lgkmcnt(1)
	v_mfma_f32_16x16x32_bf16 v[130:133], v[204:207], v[142:145], v[172:175]
	v_mfma_f32_16x16x32_bf16 v[134:137], v[212:215], v[142:145], v[176:179]
	v_mfma_f32_16x16x32_bf16 v[138:141], v[208:211], v[142:145], v[180:183]
	v_mfma_f32_16x16x32_bf16 v[142:145], v[216:219], v[142:145], v[184:187]
	s_waitcnt lgkmcnt(0)
	v_mfma_f32_16x16x32_bf16 v[146:149], v[204:207], v[158:161], v[188:191]
	v_mfma_f32_16x16x32_bf16 v[150:153], v[212:215], v[158:161], v[192:195]
	v_mfma_f32_16x16x32_bf16 v[154:157], v[208:211], v[158:161], v[196:199]
	v_mfma_f32_16x16x32_bf16 v[158:161], v[216:219], v[158:161], v[200:203]
	s_add_i32 s2, s50, -1
	s_cmp_ge_i32 s2, s46
	s_cbranch_scc1 .LBB0_614
	v_mov_b32_e32 v162, v0
	s_nop 0
	v_ashrrev_i32_e32 v167, 4, v162
	v_xor_b32_e32 v162, v167, v162
	v_lshlrev_b32_e32 v162, 4, v162
	v_and_b32_e32 v162, 0xf0, v162
	v_lshl_or_b32 v162, v167, 8, v162
	v_add_u32_e32 v162, 0x10000, v162
	s_waitcnt vmcnt(5)
	ds_write_b128 v162, v[18:21]
	ds_write_b128 v162, v[6:9] offset:8192
	ds_write_b128 v162, v[10:13] offset:16384
	s_waitcnt vmcnt(3)
	ds_write_b128 v162, v[22:25] offset:24576
	ds_write_b128 v162, v[14:17] offset:32768
	s_waitcnt vmcnt(2)
	ds_write_b128 v162, v[26:29] offset:40960
	s_waitcnt vmcnt(1)
	ds_write_b128 v162, v[30:33] offset:49152
	s_waitcnt vmcnt(0)
	ds_write_b128 v162, v[34:37] offset:57344
.LBB0_614:
	v_mov_b32_e32 v162, v0
	s_waitcnt vmcnt(7)
	v_mov_b32_e32 v6, v0
	s_waitcnt lgkmcnt(0)
	s_barrier
	s_nop 0
	v_and_b32_e32 v7, 14, v6
	v_ashrrev_i32_e32 v8, 1, v6
	v_and_or_b32 v7, v8, s51, v7
	s_waitcnt vmcnt(3)
	v_ashrrev_i32_e32 v23, 1, v7
	v_lshlrev_b32_e32 v7, 3, v6
	v_and_b32_e32 v24, 8, v7
	v_lshrrev_b32_e32 v7, 1, v6
	v_and_b32_e32 v7, 0x67, v7
	v_bfe_u32 v22, v6, 4, 2
	v_bfe_u32 v6, v6, 1, 3
	v_lshlrev_b32_e32 v8, 8, v7
	v_or_b32_e32 v9, 8, v7
	v_bitop3_b32 v7, v7, 15, 8 bitop3:0xc8
	v_or_b32_e32 v25, 8, v23
	v_bitop3_b32 v6, v24, v6, v22 bitop3:0x36
	v_bitop3_b32 v7, v24, v7, v22 bitop3:0x36
	v_or_b32_e32 v22, v24, v22
	v_bitop3_b32 v24, v23, v22, 7 bitop3:0x6c
	v_bitop3_b32 v22, v25, v22, 15 bitop3:0x6c
	v_lshlrev_b32_e32 v9, 8, v9
	v_lshlrev_b32_e32 v22, 4, v22
	v_lshl_or_b32 v14, v6, 4, v8
	v_lshl_or_b32 v15, v7, 4, v9
	v_lshlrev_b32_e32 v24, 4, v24
	v_lshl_or_b32 v22, v25, 8, v22
	v_or_b32_e32 v6, 0x18000, v14
	v_or_b32_e32 v10, 0x18000, v15
	v_or_b32_e32 v14, 0x19000, v14
	v_or_b32_e32 v18, 0x19000, v15
	v_lshl_or_b32 v23, v23, 8, v24
	v_add_u32_e32 v204, 0x10000, v22
	ds_read_b128 v[6:9], v6
	ds_read_b128 v[10:13], v10
	ds_read_b128 v[14:17], v14
	ds_read_b128 v[18:21], v18
	v_add_u32_e32 v167, 0x10000, v23
	ds_read_b128 v[22:25], v204
	s_waitcnt vmcnt(2)
	ds_read_b128 v[26:29], v167
	s_waitcnt vmcnt(1)
	ds_read_b128 v[30:33], v167 offset:4096
	s_waitcnt lgkmcnt(1)
	v_mfma_f32_16x16x32_bf16 v[2:5], v[6:9], v[26:29], v[2:5]
	s_waitcnt vmcnt(0)
	v_mfma_f32_16x16x32_bf16 v[34:37], v[10:13], v[26:29], v[38:41]
	v_mfma_f32_16x16x32_bf16 v[38:41], v[14:17], v[26:29], v[42:45]
	v_mfma_f32_16x16x32_bf16 v[26:29], v[18:21], v[26:29], v[46:49]
	v_mfma_f32_16x16x32_bf16 v[42:45], v[6:9], v[22:25], v[50:53]
	v_mfma_f32_16x16x32_bf16 v[46:49], v[10:13], v[22:25], v[54:57]
	v_mfma_f32_16x16x32_bf16 v[50:53], v[14:17], v[22:25], v[58:61]
	s_nop 1
	ds_read_b128 v[54:57], v204 offset:4096
	ds_read_b128 v[58:61], v167 offset:8192
	v_mfma_f32_16x16x32_bf16 v[22:25], v[18:21], v[22:25], v[62:65]
	s_waitcnt lgkmcnt(2)
	v_mfma_f32_16x16x32_bf16 v[62:65], v[6:9], v[30:33], v[66:69]
	v_mfma_f32_16x16x32_bf16 v[66:69], v[10:13], v[30:33], v[70:73]
	v_mfma_f32_16x16x32_bf16 v[70:73], v[14:17], v[30:33], v[74:77]
	v_mfma_f32_16x16x32_bf16 v[30:33], v[18:21], v[30:33], v[78:81]
	s_waitcnt lgkmcnt(1)
	v_mfma_f32_16x16x32_bf16 v[74:77], v[6:9], v[54:57], v[82:85]
	s_waitcnt lgkmcnt(0)
	v_mfma_f32_16x16x32_bf16 v[176:179], v[6:9], v[58:61], v[98:101]
	v_mfma_f32_16x16x32_bf16 v[180:183], v[10:13], v[58:61], v[102:105]
	v_mfma_f32_16x16x32_bf16 v[184:187], v[14:17], v[58:61], v[106:109]
	v_mfma_f32_16x16x32_bf16 v[188:191], v[18:21], v[58:61], v[110:113]
	ds_read_b128 v[58:61], v204 offset:8192
	ds_read_b128 v[78:81], v167 offset:12288
	ds_read_b128 v[82:85], v204 offset:12288
	v_mfma_f32_16x16x32_bf16 v[168:171], v[10:13], v[54:57], v[86:89]
	v_mfma_f32_16x16x32_bf16 v[172:175], v[14:17], v[54:57], v[90:93]
	v_mfma_f32_16x16x32_bf16 v[54:57], v[18:21], v[54:57], v[94:97]
	s_waitcnt lgkmcnt(2)
	v_mfma_f32_16x16x32_bf16 v[192:195], v[6:9], v[58:61], v[114:117]
	v_mfma_f32_16x16x32_bf16 v[196:199], v[10:13], v[58:61], v[118:121]
	v_mfma_f32_16x16x32_bf16 v[200:203], v[14:17], v[58:61], v[122:125]
	v_mfma_f32_16x16x32_bf16 v[204:207], v[18:21], v[58:61], v[126:129]
	s_waitcnt lgkmcnt(1)
	v_mfma_f32_16x16x32_bf16 v[130:133], v[6:9], v[78:81], v[130:133]
	v_mfma_f32_16x16x32_bf16 v[134:137], v[10:13], v[78:81], v[134:137]
	s_waitcnt lgkmcnt(0)
	v_mfma_f32_16x16x32_bf16 v[6:9], v[6:9], v[82:85], v[146:149]
	v_mfma_f32_16x16x32_bf16 v[10:13], v[10:13], v[82:85], v[150:153]
	v_mfma_f32_16x16x32_bf16 v[138:141], v[14:17], v[78:81], v[138:141]
	v_mfma_f32_16x16x32_bf16 v[142:145], v[18:21], v[78:81], v[142:145]
	v_mfma_f32_16x16x32_bf16 v[146:149], v[14:17], v[82:85], v[154:157]
	v_mfma_f32_16x16x32_bf16 v[150:153], v[18:21], v[82:85], v[158:161]
	v_mov_b32_e32 v14, v0
	s_nop 0
	v_and_b32_e32 v15, 14, v14
	v_ashrrev_i32_e32 v17, 1, v14
	v_and_or_b32 v15, v17, s51, v15
	v_lshlrev_b32_e32 v17, 3, v14
	v_bfe_u32 v16, v14, 4, 2
	v_and_b32_e32 v17, 8, v17
	v_ashrrev_i32_e32 v15, 1, v15
	v_or_b32_e32 v18, v17, v16
	v_bitop3_b32 v19, v15, v18, 7 bitop3:0x6c
	v_lshlrev_b32_e32 v20, 8, v15
	v_or_b32_e32 v15, 8, v15
	v_bitop3_b32 v18, v15, v18, 15 bitop3:0x6c
	v_lshlrev_b32_e32 v15, 8, v15
	v_lshl_or_b32 v18, v18, 4, v15
	v_lshrrev_b32_e32 v15, 1, v14
	v_and_b32_e32 v15, 0x67, v15
	v_bfe_u32 v14, v14, 1, 3
	v_lshl_or_b32 v19, v19, 4, v20
	v_bitop3_b32 v14, v17, v14, v16 bitop3:0x36
	v_lshlrev_b32_e32 v20, 8, v15
	v_lshl_or_b32 v20, v14, 4, v20
	v_or_b32_e32 v14, 8, v15
	v_bitop3_b32 v15, v15, 15, 8 bitop3:0xc8
	v_bitop3_b32 v15, v17, v15, v16 bitop3:0x36
	v_lshlrev_b32_e32 v14, 8, v14
	v_lshl_or_b32 v21, v15, 4, v14
	v_bitop3_b32 v14, v20, s52, v164 bitop3:0xde
	v_bitop3_b32 v58, v21, s52, v164 bitop3:0xde
	v_bitop3_b32 v20, v20, s53, v164 bitop3:0xde
	v_bitop3_b32 v21, v21, s53, v164 bitop3:0xde
	v_xad_u32 v212, v18, 64, v165
	ds_read_b128 v[14:17], v14
	ds_read_b128 v[154:157], v58
	ds_read_b128 v[158:161], v20
	ds_read_b128 v[208:211], v21
	v_xad_u32 v167, v19, 64, v165
	ds_read_b128 v[18:21], v212
	ds_read_b128 v[58:61], v167
	ds_read_b128 v[78:81], v167 offset:4096
	s_waitcnt lgkmcnt(1)
	v_mfma_f32_16x16x32_bf16 v[126:129], v[14:17], v[58:61], v[2:5]
	v_mfma_f32_16x16x32_bf16 v[114:117], v[208:211], v[58:61], v[26:29]
	s_nop 1
	ds_read_b128 v[2:5], v212 offset:4096
	ds_read_b128 v[26:29], v167 offset:8192
	v_mfma_f32_16x16x32_bf16 v[122:125], v[154:157], v[58:61], v[34:37]
	v_mfma_f32_16x16x32_bf16 v[118:121], v[158:161], v[58:61], v[38:41]
	v_mfma_f32_16x16x32_bf16 v[110:113], v[14:17], v[18:21], v[42:45]
	v_mfma_f32_16x16x32_bf16 v[106:109], v[154:157], v[18:21], v[46:49]
	v_mfma_f32_16x16x32_bf16 v[102:105], v[158:161], v[18:21], v[50:53]
	v_mfma_f32_16x16x32_bf16 v[98:101], v[208:211], v[18:21], v[22:25]
	s_waitcnt lgkmcnt(2)
	v_mfma_f32_16x16x32_bf16 v[94:97], v[14:17], v[78:81], v[62:65]
	v_mfma_f32_16x16x32_bf16 v[90:93], v[154:157], v[78:81], v[66:69]
	v_mfma_f32_16x16x32_bf16 v[86:89], v[158:161], v[78:81], v[70:73]
	v_mfma_f32_16x16x32_bf16 v[82:85], v[208:211], v[78:81], v[30:33]
	s_waitcnt lgkmcnt(1)
	v_mfma_f32_16x16x32_bf16 v[78:81], v[14:17], v[2:5], v[74:77]
	v_mfma_f32_16x16x32_bf16 v[74:77], v[154:157], v[2:5], v[168:171]
	v_mfma_f32_16x16x32_bf16 v[70:73], v[158:161], v[2:5], v[172:175]
	v_mfma_f32_16x16x32_bf16 v[66:69], v[208:211], v[2:5], v[54:57]
	ds_read_b128 v[2:5], v212 offset:8192
	ds_read_b128 v[18:21], v167 offset:12288
	ds_read_b128 v[168:171], v212 offset:12288
	s_waitcnt lgkmcnt(3)
	v_mfma_f32_16x16x32_bf16 v[62:65], v[14:17], v[26:29], v[176:179]
	v_mfma_f32_16x16x32_bf16 v[58:61], v[154:157], v[26:29], v[180:183]
	v_mfma_f32_16x16x32_bf16 v[54:57], v[158:161], v[26:29], v[184:187]
	v_mfma_f32_16x16x32_bf16 v[50:53], v[208:211], v[26:29], v[188:191]
	s_waitcnt lgkmcnt(2)
	v_mfma_f32_16x16x32_bf16 v[46:49], v[14:17], v[2:5], v[192:195]
	v_mfma_f32_16x16x32_bf16 v[42:45], v[154:157], v[2:5], v[196:199]
	v_mfma_f32_16x16x32_bf16 v[38:41], v[158:161], v[2:5], v[200:203]
	v_mfma_f32_16x16x32_bf16 v[34:37], v[208:211], v[2:5], v[204:207]
	s_waitcnt lgkmcnt(1)
	v_mfma_f32_16x16x32_bf16 v[30:33], v[14:17], v[18:21], v[130:133]
	v_mfma_f32_16x16x32_bf16 v[26:29], v[154:157], v[18:21], v[134:137]
	v_mfma_f32_16x16x32_bf16 v[22:25], v[158:161], v[18:21], v[138:141]
	v_mfma_f32_16x16x32_bf16 v[18:21], v[208:211], v[18:21], v[142:145]
	s_waitcnt lgkmcnt(0)
	v_mfma_f32_16x16x32_bf16 v[14:17], v[14:17], v[168:171], v[6:9]
	v_mfma_f32_16x16x32_bf16 v[10:13], v[154:157], v[168:171], v[10:13]
	v_mfma_f32_16x16x32_bf16 v[6:9], v[158:161], v[168:171], v[146:149]
	v_mfma_f32_16x16x32_bf16 v[2:5], v[208:211], v[168:171], v[150:153]
	s_cmp_ge_i32 s50, s46
	s_cselect_b64 s[28:29], -1, 0
	s_and_b64 vcc, exec, s[28:29]
	s_cbranch_vccnz .LBB0_616
	s_lshl_b32 s2, s43, 8
	s_ashr_i32 s3, s2, 31
	v_lshlrev_b32_e32 v130, 4, v162
	s_lshl_b64 s[2:3], s[2:3], 8
	v_and_b32_e32 v130, 0x70, v130
	v_lshlrev_b32_e32 v131, 5, v162
	s_add_u32 s2, s34, s2
	v_and_or_b32 v162, v131, s40, v130
	s_addc_u32 s3, s35, s3
	v_lshl_add_u64 v[138:139], s[2:3], 0, v[162:163]
	s_lshl_b32 s4, s38, 8
	v_add_co_u32_e32 v130, vcc, s44, v138
	s_ashr_i32 s5, s4, 31
	s_nop 0
	v_addc_co_u32_e32 v131, vcc, 0, v139, vcc
	s_lshl_b64 s[4:5], s[4:5], 8
	v_add_co_u32_e32 v134, vcc, s42, v138
	s_add_u32 s4, s37, s4
	s_nop 0
	v_addc_co_u32_e32 v135, vcc, 0, v139, vcc
	s_addc_u32 s5, s39, s5
	v_add_co_u32_e32 v146, vcc, s41, v138
	v_lshl_add_u64 v[154:155], s[4:5], 0, v[162:163]
	s_nop 0
	v_addc_co_u32_e32 v147, vcc, 0, v139, vcc
	v_add_co_u32_e32 v150, vcc, s44, v154
	global_load_dwordx4 v[130:133], v[130:131], off
	s_nop 0
	global_load_dwordx4 v[134:137], v[134:135], off
	v_addc_co_u32_e32 v151, vcc, 0, v155, vcc
	v_add_co_u32_e32 v156, vcc, s42, v154
	global_load_dwordx4 v[138:141], v162, s[2:3]
	global_load_dwordx4 v[142:145], v162, s[4:5]
	v_addc_co_u32_e32 v157, vcc, 0, v155, vcc
	v_add_co_u32_e32 v158, vcc, s41, v154
	global_load_dwordx4 v[146:149], v[146:147], off
	s_nop 0
	global_load_dwordx4 v[150:153], v[150:151], off
	v_addc_co_u32_e32 v159, vcc, 0, v155, vcc
	global_load_dwordx4 v[154:157], v[156:157], off
	s_nop 0
	global_load_dwordx4 v[158:161], v[158:159], off
	v_mov_b32_e32 v162, v0
	s_nop 0
	v_ashrrev_i32_e32 v167, 4, v162
	v_xor_b32_e32 v162, v167, v162
	v_lshlrev_b32_e32 v167, 8, v167
	v_lshlrev_b32_e32 v162, 4, v162
	v_and_or_b32 v162, v162, s45, v167
	s_waitcnt vmcnt(0)
	ds_write_b128 v162, v[138:141]
	ds_write_b128 v162, v[130:133] offset:8192
	ds_write_b128 v162, v[134:137] offset:16384
	ds_write_b128 v162, v[146:149] offset:24576
	ds_write_b128 v162, v[142:145] offset:32768
	ds_write_b128 v162, v[150:153] offset:40960
	ds_write_b128 v162, v[154:157] offset:49152
	ds_write_b128 v162, v[158:161] offset:57344

.LBB0_706:
	v_mov_b32_e32 v3, v0
	s_nop 0
	v_and_b32_e32 v4, 14, v3
	v_ashrrev_i32_e32 v38, 1, v3
	v_and_or_b32 v4, v38, s31, v4
	v_lshlrev_b32_e32 v38, 3, v3
	v_and_b32_e32 v54, 8, v38
	v_lshrrev_b32_e32 v38, 1, v3
	v_and_b32_e32 v38, 0x67, v38
	v_bfe_u32 v5, v3, 4, 2
	v_bfe_u32 v3, v3, 1, 3
	v_lshlrev_b32_e32 v39, 8, v38
	v_or_b32_e32 v40, 8, v38
	v_bitop3_b32 v38, v38, 15, 8 bitop3:0xc8
	v_bitop3_b32 v3, v54, v3, v5 bitop3:0x36
	v_bitop3_b32 v38, v54, v38, v5 bitop3:0x36
	v_lshlrev_b32_e32 v40, 8, v40
	v_ashrrev_i32_e32 v4, 1, v4
	v_lshl_or_b32 v3, v3, 4, v39
	v_lshl_or_b32 v50, v38, 4, v40
	v_or_b32_e32 v56, 8, v4
	ds_read_b128 v[38:41], v3 offset:32768
	ds_read_b128 v[42:45], v3 offset:36864
	ds_read_b128 v[46:49], v50 offset:32768
	ds_read_b128 v[50:53], v50 offset:36864
	v_or_b32_e32 v3, v54, v5
	v_lshlrev_b32_e32 v55, 8, v4
	v_lshlrev_b32_e32 v57, 8, v56
	v_bitop3_b32 v4, v4, v3, 7 bitop3:0x6c
	v_bitop3_b32 v3, v56, v3, 15 bitop3:0x6c
	v_lshl_or_b32 v162, v3, 4, v57
	v_lshl_or_b32 v150, v4, 4, v55
	ds_read_b128 v[54:57], v162
	ds_read_b128 v[58:61], v150
	ds_read_b128 v[62:65], v150 offset:4096
	v_mov_b32_e32 v3, v2
	v_mov_b32_e32 v4, v2
	v_mov_b32_e32 v5, v2
	ds_read_b128 v[90:93], v162 offset:4096
	ds_read_b128 v[94:97], v150 offset:8192
	s_waitcnt lgkmcnt(3)
	v_mfma_f32_16x16x32_bf16 v[66:69], v[58:61], v[38:41], v[2:5]
	v_mfma_f32_16x16x32_bf16 v[70:73], v[58:61], v[46:49], v[2:5]
	v_mfma_f32_16x16x32_bf16 v[74:77], v[58:61], v[42:45], v[2:5]
	v_mfma_f32_16x16x32_bf16 v[58:61], v[58:61], v[50:53], v[2:5]
	v_mfma_f32_16x16x32_bf16 v[78:81], v[54:57], v[38:41], v[2:5]
	v_mfma_f32_16x16x32_bf16 v[82:85], v[54:57], v[46:49], v[2:5]
	v_mfma_f32_16x16x32_bf16 v[86:89], v[54:57], v[42:45], v[2:5]
	v_mfma_f32_16x16x32_bf16 v[98:101], v[54:57], v[50:53], v[2:5]
	s_waitcnt lgkmcnt(2)
	v_mfma_f32_16x16x32_bf16 v[102:105], v[62:65], v[38:41], v[2:5]
	v_mfma_f32_16x16x32_bf16 v[106:109], v[62:65], v[46:49], v[2:5]
	v_mfma_f32_16x16x32_bf16 v[110:113], v[62:65], v[42:45], v[2:5]
	v_mfma_f32_16x16x32_bf16 v[114:117], v[62:65], v[50:53], v[2:5]
	ds_read_b128 v[54:57], v162 offset:8192
	ds_read_b128 v[62:65], v150 offset:12288
	s_waitcnt lgkmcnt(3)
	v_mfma_f32_16x16x32_bf16 v[118:121], v[90:93], v[38:41], v[2:5]
	v_mfma_f32_16x16x32_bf16 v[122:125], v[90:93], v[46:49], v[2:5]
	v_mfma_f32_16x16x32_bf16 v[126:129], v[90:93], v[42:45], v[2:5]
	v_mfma_f32_16x16x32_bf16 v[130:133], v[90:93], v[50:53], v[2:5]
	ds_read_b128 v[90:93], v162 offset:12288
	s_waitcnt lgkmcnt(3)
	v_mfma_f32_16x16x32_bf16 v[134:137], v[94:97], v[38:41], v[2:5]
	v_mfma_f32_16x16x32_bf16 v[138:141], v[94:97], v[46:49], v[2:5]
	v_mfma_f32_16x16x32_bf16 v[142:145], v[94:97], v[42:45], v[2:5]
	v_mfma_f32_16x16x32_bf16 v[146:149], v[94:97], v[50:53], v[2:5]
	s_waitcnt lgkmcnt(2)
	v_mfma_f32_16x16x32_bf16 v[150:153], v[54:57], v[38:41], v[2:5]
	v_mfma_f32_16x16x32_bf16 v[154:157], v[54:57], v[46:49], v[2:5]
	v_mfma_f32_16x16x32_bf16 v[158:161], v[54:57], v[42:45], v[2:5]
	v_mfma_f32_16x16x32_bf16 v[166:169], v[54:57], v[50:53], v[2:5]
	s_waitcnt lgkmcnt(1)
	v_mfma_f32_16x16x32_bf16 v[170:173], v[62:65], v[38:41], v[2:5]
	v_mfma_f32_16x16x32_bf16 v[174:177], v[62:65], v[46:49], v[2:5]
	v_mfma_f32_16x16x32_bf16 v[178:181], v[62:65], v[42:45], v[2:5]
	v_mfma_f32_16x16x32_bf16 v[182:185], v[62:65], v[50:53], v[2:5]
	s_waitcnt lgkmcnt(0)
	v_mfma_f32_16x16x32_bf16 v[186:189], v[90:93], v[38:41], v[2:5]
	v_mfma_f32_16x16x32_bf16 v[190:193], v[90:93], v[46:49], v[2:5]
	v_mfma_f32_16x16x32_bf16 v[194:197], v[90:93], v[42:45], v[2:5]
	v_mfma_f32_16x16x32_bf16 v[198:201], v[90:93], v[50:53], v[2:5]
	s_nop 1
	v_mov_b32_e32 v2, v0
	s_nop 0
	v_and_b32_e32 v3, 14, v2
	v_ashrrev_i32_e32 v5, 1, v2
	v_and_or_b32 v3, v5, s31, v3
	v_lshlrev_b32_e32 v5, 3, v2
	v_bfe_u32 v4, v2, 4, 2
	v_and_b32_e32 v5, 8, v5
	v_lshrrev_b32_e32 v41, 1, v2
	v_ashrrev_i32_e32 v3, 1, v3
	v_or_b32_e32 v38, v5, v4
	v_and_b32_e32 v41, 0x67, v41
	v_bfe_u32 v2, v2, 1, 3
	v_bitop3_b32 v39, v3, v38, 7 bitop3:0x6c
	v_lshlrev_b32_e32 v40, 8, v3
	v_or_b32_e32 v3, 8, v3
	v_bitop3_b32 v2, v5, v2, v4 bitop3:0x36
	v_lshlrev_b32_e32 v42, 8, v41
	v_or_b32_e32 v43, 8, v41
	v_bitop3_b32 v41, v41, 15, 8 bitop3:0xc8
	v_bitop3_b32 v38, v3, v38, 15 bitop3:0x6c
	v_lshlrev_b32_e32 v2, 4, v2
	v_bitop3_b32 v4, v5, v41, v4 bitop3:0x36
	v_lshlrev_b32_e32 v3, 8, v3
	v_lshlrev_b32_e32 v38, 4, v38
	v_lshlrev_b32_e32 v5, 8, v43
	v_lshlrev_b32_e32 v4, 4, v4
	v_bitop3_b32 v2, v2, 64, v42 bitop3:0x36
	v_lshlrev_b32_e32 v39, 4, v39
	v_bitop3_b32 v4, v4, 64, v5 bitop3:0x36
	ds_read_b128 v[202:205], v2 offset:32768
	ds_read_b128 v[206:209], v2 offset:36864
	ds_read_b128 v[210:213], v4 offset:32768
	ds_read_b128 v[214:217], v4 offset:36864
	v_bitop3_b32 v165, v38, 64, v3 bitop3:0x36
	v_bitop3_b32 v162, v39, 64, v40 bitop3:0x36
	ds_read_b128 v[62:65], v165
	ds_read_b128 v[46:49], v162
	ds_read_b128 v[90:93], v162 offset:4096
	ds_read_b128 v[94:97], v165 offset:4096
	ds_read_b128 v[218:221], v162 offset:8192
	s_waitcnt lgkmcnt(3)
	v_mfma_f32_16x16x32_bf16 v[2:5], v[46:49], v[202:205], v[66:69]
	v_mfma_f32_16x16x32_bf16 v[38:41], v[46:49], v[210:213], v[70:73]
	v_mfma_f32_16x16x32_bf16 v[42:45], v[46:49], v[206:209], v[74:77]
	v_mfma_f32_16x16x32_bf16 v[46:49], v[46:49], v[214:217], v[58:61]
	v_mfma_f32_16x16x32_bf16 v[50:53], v[62:65], v[202:205], v[78:81]
	v_mfma_f32_16x16x32_bf16 v[54:57], v[62:65], v[210:213], v[82:85]
	v_mfma_f32_16x16x32_bf16 v[58:61], v[62:65], v[206:209], v[86:89]
	v_mfma_f32_16x16x32_bf16 v[62:65], v[62:65], v[214:217], v[98:101]
	s_waitcnt lgkmcnt(2)
	v_mfma_f32_16x16x32_bf16 v[66:69], v[90:93], v[202:205], v[102:105]
	v_mfma_f32_16x16x32_bf16 v[70:73], v[90:93], v[210:213], v[106:109]
	v_mfma_f32_16x16x32_bf16 v[74:77], v[90:93], v[206:209], v[110:113]
	v_mfma_f32_16x16x32_bf16 v[78:81], v[90:93], v[214:217], v[114:117]
	s_waitcnt lgkmcnt(1)
	v_mfma_f32_16x16x32_bf16 v[90:93], v[94:97], v[206:209], v[126:129]
	s_waitcnt lgkmcnt(0)
	v_mfma_f32_16x16x32_bf16 v[106:109], v[218:221], v[206:209], v[142:145]
	s_nop 0
	ds_read_b128 v[126:129], v165 offset:8192
	s_nop 0
	ds_read_b128 v[142:145], v162 offset:12288
	v_mfma_f32_16x16x32_bf16 v[86:89], v[94:97], v[210:213], v[122:125]
	s_waitcnt lgkmcnt(1)
	v_mfma_f32_16x16x32_bf16 v[122:125], v[126:129], v[206:209], v[158:161]
	s_nop 2
	ds_read_b128 v[158:161], v165 offset:12288
	v_mfma_f32_16x16x32_bf16 v[82:85], v[94:97], v[202:205], v[118:121]
	v_mfma_f32_16x16x32_bf16 v[94:97], v[94:97], v[214:217], v[130:133]
	v_mfma_f32_16x16x32_bf16 v[98:101], v[218:221], v[202:205], v[134:137]
	v_mfma_f32_16x16x32_bf16 v[102:105], v[218:221], v[210:213], v[138:141]
	v_mfma_f32_16x16x32_bf16 v[110:113], v[218:221], v[214:217], v[146:149]
	v_mfma_f32_16x16x32_bf16 v[114:117], v[126:129], v[202:205], v[150:153]
	v_mfma_f32_16x16x32_bf16 v[118:121], v[126:129], v[210:213], v[154:157]
	v_mfma_f32_16x16x32_bf16 v[126:129], v[126:129], v[214:217], v[166:169]
	s_waitcnt lgkmcnt(1)
	v_mfma_f32_16x16x32_bf16 v[130:133], v[142:145], v[202:205], v[170:173]
	v_mfma_f32_16x16x32_bf16 v[134:137], v[142:145], v[210:213], v[174:177]
	v_mfma_f32_16x16x32_bf16 v[138:141], v[142:145], v[206:209], v[178:181]
	v_mfma_f32_16x16x32_bf16 v[142:145], v[142:145], v[214:217], v[182:185]
	s_waitcnt lgkmcnt(0)
	v_mfma_f32_16x16x32_bf16 v[146:149], v[158:161], v[202:205], v[186:189]
	v_mfma_f32_16x16x32_bf16 v[150:153], v[158:161], v[210:213], v[190:193]
	v_mfma_f32_16x16x32_bf16 v[154:157], v[158:161], v[206:209], v[194:197]
	v_mfma_f32_16x16x32_bf16 v[158:161], v[158:161], v[214:217], v[198:201]
	s_add_i32 s6, s30, -1
	s_cmp_ge_i32 s6, s28
	s_cbranch_scc1 .LBB0_708
	v_mov_b32_e32 v162, v0
	s_nop 0
	v_ashrrev_i32_e32 v165, 4, v162
	v_xor_b32_e32 v162, v165, v162
	v_lshlrev_b32_e32 v162, 4, v162
	v_and_b32_e32 v162, 0xf0, v162
	v_lshl_or_b32 v162, v165, 8, v162
	v_add_u32_e32 v162, 0x10000, v162
	s_waitcnt vmcnt(5)
	ds_write_b128 v162, v[18:21]
	ds_write_b128 v162, v[6:9] offset:8192
	ds_write_b128 v162, v[10:13] offset:16384
	s_waitcnt vmcnt(3)
	ds_write_b128 v162, v[22:25] offset:24576
	ds_write_b128 v162, v[14:17] offset:32768
	s_waitcnt vmcnt(2)
	ds_write_b128 v162, v[26:29] offset:40960
	s_waitcnt vmcnt(1)
	ds_write_b128 v162, v[30:33] offset:49152
	s_waitcnt vmcnt(0)
	ds_write_b128 v162, v[34:37] offset:57344
.LBB0_708:
	v_mov_b32_e32 v162, v0
	s_waitcnt vmcnt(7)
	v_mov_b32_e32 v6, v0
	s_waitcnt lgkmcnt(0)
	s_barrier
	s_nop 0
	v_and_b32_e32 v7, 14, v6
	v_ashrrev_i32_e32 v8, 1, v6
	v_and_or_b32 v7, v8, s31, v7
	s_waitcnt vmcnt(3)
	v_ashrrev_i32_e32 v23, 1, v7
	v_lshlrev_b32_e32 v7, 3, v6
	v_and_b32_e32 v24, 8, v7
	v_lshrrev_b32_e32 v7, 1, v6
	v_and_b32_e32 v7, 0x67, v7
	v_bfe_u32 v22, v6, 4, 2
	v_bfe_u32 v6, v6, 1, 3
	v_lshlrev_b32_e32 v8, 8, v7
	v_or_b32_e32 v9, 8, v7
	v_bitop3_b32 v7, v7, 15, 8 bitop3:0xc8
	v_or_b32_e32 v25, 8, v23
	v_bitop3_b32 v6, v24, v6, v22 bitop3:0x36
	v_bitop3_b32 v7, v24, v7, v22 bitop3:0x36
	v_or_b32_e32 v22, v24, v22
	v_bitop3_b32 v24, v23, v22, 7 bitop3:0x6c
	v_bitop3_b32 v22, v25, v22, 15 bitop3:0x6c
	v_lshlrev_b32_e32 v9, 8, v9
	v_lshlrev_b32_e32 v22, 4, v22
	v_lshl_or_b32 v14, v6, 4, v8
	v_lshl_or_b32 v15, v7, 4, v9
	v_lshlrev_b32_e32 v24, 4, v24
	v_lshl_or_b32 v22, v25, 8, v22
	v_or_b32_e32 v6, 0x18000, v14
	v_or_b32_e32 v10, 0x18000, v15
	v_or_b32_e32 v14, 0x19000, v14
	v_or_b32_e32 v18, 0x19000, v15
	v_lshl_or_b32 v23, v23, 8, v24
	v_add_u32_e32 v202, 0x10000, v22
	ds_read_b128 v[6:9], v6
	ds_read_b128 v[10:13], v10
	ds_read_b128 v[14:17], v14
	ds_read_b128 v[18:21], v18
	v_add_u32_e32 v165, 0x10000, v23
	ds_read_b128 v[22:25], v202
	s_waitcnt vmcnt(2)
	ds_read_b128 v[26:29], v165
	s_waitcnt vmcnt(1)
	ds_read_b128 v[30:33], v165 offset:4096
	s_waitcnt lgkmcnt(1)
	v_mfma_f32_16x16x32_bf16 v[2:5], v[26:29], v[6:9], v[2:5]
	s_waitcnt vmcnt(0)
	v_mfma_f32_16x16x32_bf16 v[34:37], v[26:29], v[10:13], v[38:41]
	v_mfma_f32_16x16x32_bf16 v[38:41], v[26:29], v[14:17], v[42:45]
	v_mfma_f32_16x16x32_bf16 v[26:29], v[26:29], v[18:21], v[46:49]
	v_mfma_f32_16x16x32_bf16 v[42:45], v[22:25], v[6:9], v[50:53]
	v_mfma_f32_16x16x32_bf16 v[46:49], v[22:25], v[10:13], v[54:57]
	v_mfma_f32_16x16x32_bf16 v[50:53], v[22:25], v[14:17], v[58:61]
	s_nop 1
	ds_read_b128 v[54:57], v202 offset:4096
	ds_read_b128 v[58:61], v165 offset:8192
	v_mfma_f32_16x16x32_bf16 v[22:25], v[22:25], v[18:21], v[62:65]
	s_waitcnt lgkmcnt(2)
	v_mfma_f32_16x16x32_bf16 v[62:65], v[30:33], v[6:9], v[66:69]
	v_mfma_f32_16x16x32_bf16 v[66:69], v[30:33], v[10:13], v[70:73]
	v_mfma_f32_16x16x32_bf16 v[70:73], v[30:33], v[14:17], v[74:77]
	v_mfma_f32_16x16x32_bf16 v[30:33], v[30:33], v[18:21], v[78:81]
	s_waitcnt lgkmcnt(1)
	v_mfma_f32_16x16x32_bf16 v[74:77], v[54:57], v[6:9], v[82:85]
	s_waitcnt lgkmcnt(0)
	v_mfma_f32_16x16x32_bf16 v[174:177], v[58:61], v[6:9], v[98:101]
	v_mfma_f32_16x16x32_bf16 v[178:181], v[58:61], v[10:13], v[102:105]
	v_mfma_f32_16x16x32_bf16 v[182:185], v[58:61], v[14:17], v[106:109]
	v_mfma_f32_16x16x32_bf16 v[186:189], v[58:61], v[18:21], v[110:113]
	ds_read_b128 v[58:61], v202 offset:8192
	ds_read_b128 v[78:81], v165 offset:12288
	ds_read_b128 v[82:85], v202 offset:12288
	v_mfma_f32_16x16x32_bf16 v[166:169], v[54:57], v[10:13], v[86:89]
	v_mfma_f32_16x16x32_bf16 v[170:173], v[54:57], v[14:17], v[90:93]
	v_mfma_f32_16x16x32_bf16 v[54:57], v[54:57], v[18:21], v[94:97]
	s_waitcnt lgkmcnt(2)
	v_mfma_f32_16x16x32_bf16 v[190:193], v[58:61], v[6:9], v[114:117]
	v_mfma_f32_16x16x32_bf16 v[194:197], v[58:61], v[10:13], v[118:121]
	v_mfma_f32_16x16x32_bf16 v[198:201], v[58:61], v[14:17], v[122:125]
	v_mfma_f32_16x16x32_bf16 v[202:205], v[58:61], v[18:21], v[126:129]
	s_waitcnt lgkmcnt(1)
	v_mfma_f32_16x16x32_bf16 v[130:133], v[78:81], v[6:9], v[130:133]
	v_mfma_f32_16x16x32_bf16 v[134:137], v[78:81], v[10:13], v[134:137]
	s_waitcnt lgkmcnt(0)
	v_mfma_f32_16x16x32_bf16 v[6:9], v[82:85], v[6:9], v[146:149]
	v_mfma_f32_16x16x32_bf16 v[10:13], v[82:85], v[10:13], v[150:153]
	v_mfma_f32_16x16x32_bf16 v[138:141], v[78:81], v[14:17], v[138:141]
	v_mfma_f32_16x16x32_bf16 v[142:145], v[78:81], v[18:21], v[142:145]
	v_mfma_f32_16x16x32_bf16 v[146:149], v[82:85], v[14:17], v[154:157]
	v_mfma_f32_16x16x32_bf16 v[150:153], v[82:85], v[18:21], v[158:161]
	v_mov_b32_e32 v14, v0
	s_nop 0
	v_and_b32_e32 v15, 14, v14
	v_ashrrev_i32_e32 v17, 1, v14
	v_and_or_b32 v15, v17, s31, v15
	v_lshlrev_b32_e32 v17, 3, v14
	v_bfe_u32 v16, v14, 4, 2
	v_and_b32_e32 v17, 8, v17
	v_ashrrev_i32_e32 v15, 1, v15
	v_or_b32_e32 v18, v17, v16
	v_bitop3_b32 v19, v15, v18, 7 bitop3:0x6c
	v_lshlrev_b32_e32 v20, 8, v15
	v_or_b32_e32 v15, 8, v15
	v_bitop3_b32 v18, v15, v18, 15 bitop3:0x6c
	v_lshlrev_b32_e32 v15, 8, v15
	v_lshl_or_b32 v18, v18, 4, v15
	v_lshrrev_b32_e32 v15, 1, v14
	v_and_b32_e32 v15, 0x67, v15
	v_bfe_u32 v14, v14, 1, 3
	v_lshl_or_b32 v19, v19, 4, v20
	v_bitop3_b32 v14, v17, v14, v16 bitop3:0x36
	v_lshlrev_b32_e32 v20, 8, v15
	v_lshl_or_b32 v20, v14, 4, v20
	v_or_b32_e32 v14, 8, v15
	v_bitop3_b32 v15, v15, 15, 8 bitop3:0xc8
	v_bitop3_b32 v15, v17, v15, v16 bitop3:0x36
	v_lshlrev_b32_e32 v14, 8, v14
	v_lshl_or_b32 v21, v15, 4, v14
	v_bitop3_b32 v14, v20, s33, v1 bitop3:0xde
	v_bitop3_b32 v58, v21, s33, v1 bitop3:0xde
	v_bitop3_b32 v20, v20, s36, v1 bitop3:0xde
	v_bitop3_b32 v21, v21, s36, v1 bitop3:0xde
	v_xad_u32 v210, v18, 64, v164
	ds_read_b128 v[14:17], v14
	ds_read_b128 v[154:157], v58
	ds_read_b128 v[158:161], v20
	ds_read_b128 v[206:209], v21
	v_xad_u32 v165, v19, 64, v164
	ds_read_b128 v[18:21], v210
	ds_read_b128 v[58:61], v165
	ds_read_b128 v[78:81], v165 offset:4096
	s_waitcnt lgkmcnt(1)
	v_mfma_f32_16x16x32_bf16 v[126:129], v[58:61], v[14:17], v[2:5]
	v_mfma_f32_16x16x32_bf16 v[114:117], v[58:61], v[206:209], v[26:29]
	s_nop 1
	ds_read_b128 v[2:5], v210 offset:4096
	ds_read_b128 v[26:29], v165 offset:8192
	v_mfma_f32_16x16x32_bf16 v[122:125], v[58:61], v[154:157], v[34:37]
	v_mfma_f32_16x16x32_bf16 v[118:121], v[58:61], v[158:161], v[38:41]
	v_mfma_f32_16x16x32_bf16 v[110:113], v[18:21], v[14:17], v[42:45]
	v_mfma_f32_16x16x32_bf16 v[106:109], v[18:21], v[154:157], v[46:49]
	v_mfma_f32_16x16x32_bf16 v[102:105], v[18:21], v[158:161], v[50:53]
	v_mfma_f32_16x16x32_bf16 v[98:101], v[18:21], v[206:209], v[22:25]
	s_waitcnt lgkmcnt(2)
	v_mfma_f32_16x16x32_bf16 v[94:97], v[78:81], v[14:17], v[62:65]
	v_mfma_f32_16x16x32_bf16 v[90:93], v[78:81], v[154:157], v[66:69]
	v_mfma_f32_16x16x32_bf16 v[86:89], v[78:81], v[158:161], v[70:73]
	v_mfma_f32_16x16x32_bf16 v[82:85], v[78:81], v[206:209], v[30:33]
	s_waitcnt lgkmcnt(1)
	v_mfma_f32_16x16x32_bf16 v[78:81], v[2:5], v[14:17], v[74:77]
	v_mfma_f32_16x16x32_bf16 v[74:77], v[2:5], v[154:157], v[166:169]
	v_mfma_f32_16x16x32_bf16 v[70:73], v[2:5], v[158:161], v[170:173]
	v_mfma_f32_16x16x32_bf16 v[66:69], v[2:5], v[206:209], v[54:57]
	ds_read_b128 v[2:5], v210 offset:8192
	ds_read_b128 v[18:21], v165 offset:12288
	ds_read_b128 v[166:169], v210 offset:12288
	s_waitcnt lgkmcnt(3)
	v_mfma_f32_16x16x32_bf16 v[62:65], v[26:29], v[14:17], v[174:177]
	v_mfma_f32_16x16x32_bf16 v[58:61], v[26:29], v[154:157], v[178:181]
	v_mfma_f32_16x16x32_bf16 v[54:57], v[26:29], v[158:161], v[182:185]
	v_mfma_f32_16x16x32_bf16 v[50:53], v[26:29], v[206:209], v[186:189]
	s_waitcnt lgkmcnt(2)
	v_mfma_f32_16x16x32_bf16 v[46:49], v[2:5], v[14:17], v[190:193]
	v_mfma_f32_16x16x32_bf16 v[42:45], v[2:5], v[154:157], v[194:197]
	v_mfma_f32_16x16x32_bf16 v[38:41], v[2:5], v[158:161], v[198:201]
	v_mfma_f32_16x16x32_bf16 v[34:37], v[2:5], v[206:209], v[202:205]
	s_waitcnt lgkmcnt(1)
	v_mfma_f32_16x16x32_bf16 v[30:33], v[18:21], v[14:17], v[130:133]
	v_mfma_f32_16x16x32_bf16 v[26:29], v[18:21], v[154:157], v[134:137]
	v_mfma_f32_16x16x32_bf16 v[22:25], v[18:21], v[158:161], v[138:141]
	v_mfma_f32_16x16x32_bf16 v[18:21], v[18:21], v[206:209], v[142:145]
	s_waitcnt lgkmcnt(0)
	v_mfma_f32_16x16x32_bf16 v[14:17], v[166:169], v[14:17], v[6:9]
	v_mfma_f32_16x16x32_bf16 v[10:13], v[166:169], v[154:157], v[10:13]
	v_mfma_f32_16x16x32_bf16 v[6:9], v[166:169], v[158:161], v[146:149]
	v_mfma_f32_16x16x32_bf16 v[2:5], v[166:169], v[206:209], v[150:153]
	s_cmp_ge_i32 s30, s28
	s_cselect_b64 s[6:7], -1, 0
	s_and_b64 vcc, exec, s[6:7]
	s_cbranch_vccnz .LBB0_710
	s_lshl_b32 s40, s39, 8
	s_ashr_i32 s41, s40, 31
	v_lshlrev_b32_e32 v130, 4, v162
	s_lshl_b64 s[40:41], s[40:41], 8
	v_and_b32_e32 v130, 0x70, v130
	v_lshlrev_b32_e32 v131, 5, v162
	s_add_u32 s40, s34, s40
	v_and_or_b32 v162, v131, s22, v130
	s_addc_u32 s41, s35, s41
	v_lshl_add_u64 v[138:139], s[40:41], 0, v[162:163]
	s_lshl_b32 s42, s38, 8
	v_add_co_u32_e32 v130, vcc, s25, v138
	s_ashr_i32 s43, s42, 31
	s_nop 0
	v_addc_co_u32_e32 v131, vcc, 0, v139, vcc
	s_lshl_b64 s[42:43], s[42:43], 8
	v_add_co_u32_e32 v134, vcc, s24, v138
	s_add_u32 s42, s15, s42
	s_nop 0
	v_addc_co_u32_e32 v135, vcc, 0, v139, vcc
	s_addc_u32 s43, s20, s43
	v_add_co_u32_e32 v146, vcc, s23, v138
	v_lshl_add_u64 v[154:155], s[42:43], 0, v[162:163]
	s_nop 0
	v_addc_co_u32_e32 v147, vcc, 0, v139, vcc
	v_add_co_u32_e32 v150, vcc, s25, v154
	global_load_dwordx4 v[130:133], v[130:131], off
	s_nop 0
	global_load_dwordx4 v[134:137], v[134:135], off
	v_addc_co_u32_e32 v151, vcc, 0, v155, vcc
	v_add_co_u32_e32 v156, vcc, s24, v154
	global_load_dwordx4 v[138:141], v162, s[40:41]
	global_load_dwordx4 v[142:145], v162, s[42:43]
	v_addc_co_u32_e32 v157, vcc, 0, v155, vcc
	v_add_co_u32_e32 v158, vcc, s23, v154
	global_load_dwordx4 v[146:149], v[146:147], off
	s_nop 0
	global_load_dwordx4 v[150:153], v[150:151], off
	v_addc_co_u32_e32 v159, vcc, 0, v155, vcc
	global_load_dwordx4 v[154:157], v[156:157], off
	s_nop 0
	global_load_dwordx4 v[158:161], v[158:159], off
	v_mov_b32_e32 v162, v0
	s_nop 0
	v_ashrrev_i32_e32 v165, 4, v162
	v_xor_b32_e32 v162, v165, v162
	v_lshlrev_b32_e32 v165, 8, v165
	v_lshlrev_b32_e32 v162, 4, v162
	v_and_or_b32 v162, v162, s27, v165
	s_waitcnt vmcnt(5)
	ds_write_b128 v162, v[138:141]
	ds_write_b128 v162, v[130:133] offset:8192
	ds_write_b128 v162, v[134:137] offset:16384
	s_waitcnt vmcnt(3)
	ds_write_b128 v162, v[146:149] offset:24576
	ds_write_b128 v162, v[142:145] offset:32768
	s_waitcnt vmcnt(2)
	ds_write_b128 v162, v[150:153] offset:40960
	s_waitcnt vmcnt(1)
	ds_write_b128 v162, v[154:157] offset:49152
	s_waitcnt vmcnt(0)
	ds_write_b128 v162, v[158:161] offset:57344

.LBB0_717:
	s_setprio 0
	s_cmp_gt_i32 s18, 5
	s_waitcnt lgkmcnt(0)
	s_cselect_b64 s[20:21], -1, 0
	s_cmp_lt_i32 s19, 6
	s_cselect_b64 s[2:3], -1, 0
	s_or_b64 s[2:3], s[20:21], s[2:3]
	s_and_b64 vcc, exec, s[2:3]
	s_cbranch_vccnz .LBB0_899
	s_andn2_b64 vcc, exec, s[8:9]
	s_cbranch_vccnz .LBB0_720
	s_cbranch_execz .LBB0_721
	s_branch .LBB0_774

.LBB0_1679:
	v_readfirstlane_b32 s99, v0
	s_cmp_lt_u32 s99, 0x100
	s_cbranch_scc1 .Lprio_skip13
	s_setprio 1
.Lprio_skip13:
	s_cmp_gt_i32 s18, 13
	s_cselect_b64 s[8:9], -1, 0
	s_cmp_lt_i32 s19, 14
	s_cselect_b64 s[2:3], -1, 0
	s_or_b64 s[2:3], s[8:9], s[2:3]
	s_and_b64 vcc, exec, s[2:3]
	s_cbranch_vccnz .LBB0_1960
	s_andn2_b64 vcc, exec, s[20:21]
	s_cbranch_vccnz .LBB0_1682
	s_cbranch_execz .LBB0_1683
	s_branch .LBB0_1736

.LBB0_1960:
	s_setprio 0
	s_cmp_gt_i32 s18, 14
	s_waitcnt lgkmcnt(0)
	s_cselect_b64 s[20:21], -1, 0
	s_cmp_lt_i32 s19, 15
	s_cselect_b64 s[2:3], -1, 0
	s_or_b64 s[2:3], s[20:21], s[2:3]
	s_and_b64 vcc, exec, s[2:3]
	s_cbranch_vccnz .LBB0_2142
	s_andn2_b64 vcc, exec, s[8:9]
	s_cbranch_vccnz .LBB0_1963
	s_cbranch_execz .LBB0_1964
	s_branch .LBB0_2017
